# v33 + gla_a item prologue de-serialised: 21 loads issued together into free VGPRs, consumers after with counted vmcnt
# speedup vs baseline: 1.0264x; 1.0000x over previous
; DEV void gla_load_vtg(const bf16_t* proj, int t0, int h, GlaSmemM* s) {
;   const int tid = threadIdx.x;
; #pragma unroll
;   for (int i = 0; i < 4; ++i) {
;     const int id = tid + 256 * i, c = id & 63, ec = id >> 6;
;     const uint4 u = *(const uint4*)(proj + (size_t)(t0 + c) * GLA_LD + 512 + h * 128 + ec * 8);
; DEV void phase_gla_a(const Params& p, char* smem) {
;     ...
;   for (int item = blockIdx.x; item < 768 * 4; item += gridDim.x) {
;     const int gch = item >> 2, h = item & 3, t0 = gch * 64;
;     __syncthreads();
;     gla_load_vtg(proj, t0, h, s);
.LBB0_769:
	s_lshl_b32 s19, s66, 4
	s_andn2_b32 s19, s19, 63
	v_or_b32_e32 v2, s19, v182
	v_mov_b64_e32 v[0:1], s[0:1]
	s_and_b32 s18, s66, 3
	v_mad_i64_i32 v[2:3], s[68:69], v2, s59, v[0:1]
	s_lshl_b32 s68, s18, 8
	s_mov_b32 s69, s63
	v_lshl_add_u64 v[6:7], v[2:3], 0, s[68:69]
	v_mov_b32_e32 v57, v33
	v_lshl_add_u64 v[2:3], v[6:7], 0, v[56:57]
	s_waitcnt vmcnt(63) expcnt(7) lgkmcnt(15)
	s_barrier
; DEV float bf2f(bf16_t b) { return __uint_as_float(((unsigned)b) << 16); }
; DEV void gla_load_vtg(const bf16_t* proj, int t0, int h, GlaSmemM* s) {
;   const int tid = threadIdx.x;
; #pragma unroll
;   for (int i = 0; i < 4; ++i) {
;     const int id = tid + 256 * i, c = id & 63, ec = id >> 6;
;     const uint4 u = *(const uint4*)(proj + (size_t)(t0 + c) * GLA_LD + 512 + h * 128 + ec * 8);
;     const unsigned w[4] = {u.x, u.y, u.z, u.w};
; #pragma unroll
;     for (int j = 0; j < 4; ++j) {
;       s->VT[(ec * 8 + 2 * j) * GL + c] = (bf16_t)(w[j] & 0xffffu);
;       s->VT[(ec * 8 + 2 * j + 1) * GL + c] = (bf16_t)(w[j] >> 16);
;     }
;   }
;   {
;     const int c = tid >> 2, part = tid & 3;
;     const uint4 u = *(const uint4*)(proj + (size_t)(t0 + c) * GLA_LD + 1536 + part * 8);
;     float v[8];
;     unpack8(u, v);
; #pragma unroll
;     for (int j = 0; j < 8; ++j) s->gd[c * 32 + part * 8 + j] = v[j];
;   }
; DEV void phase_gla_a(const Params& p, char* smem) {
;     ...
;     float kf[16];
;     {
;       const int d = tid & 63, cq = tid >> 6;
; #pragma unroll
;       for (int i = 0; i < 16; ++i) kf[i] = bf2f(proj[(size_t)(t0 + cq * 16 + i) * GLA_LD + 256 + h * 64 + d]);
;     }
;     __syncthreads();
	global_load_dwordx4 v[128:131], v[2:3], off offset:1024
	v_mov_b32_e32 v59, v33
	v_mov_b32_e32 v61, v33
	v_mov_b32_e32 v63, v33
	s_lshl_b32 s62, s18, 7
	v_mov_b32_e32 v65, v33
	s_ashr_i32 s67, s66, 31
	s_mov_b32 s61, 0
	s_mov_b64 s[84:85], -1
	v_lshl_add_u64 v[2:3], v[6:7], 0, v[58:59]
	global_load_dwordx4 v[132:135], v[2:3], off offset:1024
	v_lshl_add_u64 v[2:3], v[6:7], 0, v[60:61]
	global_load_dwordx4 v[136:139], v[2:3], off offset:1024
	v_lshl_add_u64 v[2:3], v[6:7], 0, v[62:63]
	global_load_dwordx4 v[140:143], v[2:3], off offset:1024
	v_add_u32_e32 v2, s19, v220
	v_mad_i64_i32 v[2:3], s[68:69], v2, s59, v[52:53]
	global_load_dwordx4 v[144:147], v[2:3], off offset:3072
	s_and_b32 s19, s66, 0xffffffc
	v_add_lshl_u32 v6, s19, v226, 4
	v_mad_i64_i32 v[2:3], s[68:69], v6, s59, v[0:1]
	v_or_b32_e32 v4, 1, v6
	v_lshl_add_u64 v[2:3], v[2:3], 0, s[62:63]
	v_mad_i64_i32 v[4:5], s[68:69], v4, s59, v[0:1]
	v_lshl_add_u64 v[2:3], v[2:3], 0, v[64:65]
	v_lshl_add_u64 v[4:5], v[4:5], 0, s[62:63]
	v_lshl_add_u64 v[4:5], v[4:5], 0, v[64:65]
	global_load_ushort v148, v[2:3], off offset:512
	global_load_ushort v149, v[4:5], off offset:512
	v_or_b32_e32 v4, 3, v6
	v_mad_i64_i32 v[4:5], s[68:69], v4, s59, v[0:1]
	v_lshl_add_u64 v[4:5], v[4:5], 0, s[62:63]
	v_lshl_add_u64 v[4:5], v[4:5], 0, v[64:65]
	v_or_b32_e32 v2, 2, v6
	v_mad_i64_i32 v[2:3], s[68:69], v2, s59, v[0:1]
	v_lshl_add_u64 v[2:3], v[2:3], 0, s[62:63]
	v_lshl_add_u64 v[2:3], v[2:3], 0, v[64:65]
	global_load_ushort v150, v[2:3], off offset:512
	global_load_ushort v151, v[4:5], off offset:512
	v_or_b32_e32 v4, 5, v6
	v_mad_i64_i32 v[4:5], s[68:69], v4, s59, v[0:1]
	v_lshl_add_u64 v[4:5], v[4:5], 0, s[62:63]
	v_lshl_add_u64 v[4:5], v[4:5], 0, v[64:65]
	v_or_b32_e32 v2, 4, v6
	v_mad_i64_i32 v[2:3], s[68:69], v2, s59, v[0:1]
	v_lshl_add_u64 v[2:3], v[2:3], 0, s[62:63]
	v_lshl_add_u64 v[2:3], v[2:3], 0, v[64:65]
	global_load_ushort v152, v[2:3], off offset:512
	global_load_ushort v153, v[4:5], off offset:512
	v_or_b32_e32 v4, 7, v6
	v_mad_i64_i32 v[4:5], s[68:69], v4, s59, v[0:1]
	v_lshl_add_u64 v[4:5], v[4:5], 0, s[62:63]
	v_lshl_add_u64 v[4:5], v[4:5], 0, v[64:65]
	v_or_b32_e32 v2, 6, v6
	v_mad_i64_i32 v[2:3], s[68:69], v2, s59, v[0:1]
	v_lshl_add_u64 v[2:3], v[2:3], 0, s[62:63]
	v_lshl_add_u64 v[2:3], v[2:3], 0, v[64:65]
	global_load_ushort v154, v[2:3], off offset:512
	global_load_ushort v155, v[4:5], off offset:512
	v_or_b32_e32 v4, 9, v6
	v_mad_i64_i32 v[4:5], s[68:69], v4, s59, v[0:1]
	v_lshl_add_u64 v[4:5], v[4:5], 0, s[62:63]
	v_lshl_add_u64 v[4:5], v[4:5], 0, v[64:65]
	v_or_b32_e32 v2, 8, v6
	v_mad_i64_i32 v[2:3], s[68:69], v2, s59, v[0:1]
	v_lshl_add_u64 v[2:3], v[2:3], 0, s[62:63]
	v_lshl_add_u64 v[2:3], v[2:3], 0, v[64:65]
	global_load_ushort v156, v[2:3], off offset:512
	global_load_ushort v157, v[4:5], off offset:512
	v_or_b32_e32 v4, 11, v6
	v_mad_i64_i32 v[4:5], s[68:69], v4, s59, v[0:1]
	v_lshl_add_u64 v[4:5], v[4:5], 0, s[62:63]
	v_lshl_add_u64 v[4:5], v[4:5], 0, v[64:65]
	v_or_b32_e32 v2, 10, v6
	v_mad_i64_i32 v[2:3], s[68:69], v2, s59, v[0:1]
	v_lshl_add_u64 v[2:3], v[2:3], 0, s[62:63]
	v_lshl_add_u64 v[2:3], v[2:3], 0, v[64:65]
	global_load_ushort v158, v[2:3], off offset:512
	global_load_ushort v159, v[4:5], off offset:512
	v_or_b32_e32 v4, 13, v6
	v_mad_i64_i32 v[4:5], s[68:69], v4, s59, v[0:1]
	v_lshl_add_u64 v[4:5], v[4:5], 0, s[62:63]
	v_lshl_add_u64 v[4:5], v[4:5], 0, v[64:65]
	v_or_b32_e32 v2, 12, v6
	v_mad_i64_i32 v[2:3], s[68:69], v2, s59, v[0:1]
	v_lshl_add_u64 v[2:3], v[2:3], 0, s[62:63]
	v_lshl_add_u64 v[2:3], v[2:3], 0, v[64:65]
	global_load_ushort v160, v[2:3], off offset:512
	global_load_ushort v161, v[4:5], off offset:512
	v_or_b32_e32 v4, 15, v6
	v_or_b32_e32 v2, 14, v6
	v_mad_i64_i32 v[2:3], s[68:69], v2, s59, v[0:1]
	v_mad_i64_i32 v[0:1], s[68:69], v4, s59, v[0:1]
	v_lshl_add_u64 v[2:3], v[2:3], 0, s[62:63]
	v_lshl_add_u64 v[0:1], v[0:1], 0, s[62:63]
	v_lshl_add_u64 v[2:3], v[2:3], 0, v[64:65]
	v_lshl_add_u64 v[0:1], v[0:1], 0, v[64:65]
	global_load_ushort v162, v[2:3], off offset:512
	global_load_ushort v163, v[0:1], off offset:512
	s_lshl_b64 s[68:69], s[66:67], 1
	v_lshl_or_b32 v0, s18, 6, v182
	v_lshlrev_b32_e32 v32, 2, v0
	s_waitcnt vmcnt(20)
	ds_write_b16 v96, v128
	ds_write_b16_d16_hi v96, v128 offset:144
	ds_write_b16 v96, v129 offset:288
	ds_write_b16_d16_hi v96, v129 offset:432
	ds_write_b16 v96, v130 offset:576
	ds_write_b16_d16_hi v96, v130 offset:720
	ds_write_b16 v96, v131 offset:864
	ds_write_b16_d16_hi v96, v131 offset:1008
	s_waitcnt vmcnt(19)
	ds_write_b16 v97, v132
	ds_write_b16_d16_hi v97, v132 offset:144
	ds_write_b16 v97, v133 offset:288
	ds_write_b16_d16_hi v97, v133 offset:432
	ds_write_b16 v97, v134 offset:576
	ds_write_b16_d16_hi v97, v134 offset:720
	ds_write_b16 v97, v135 offset:864
	ds_write_b16_d16_hi v97, v135 offset:1008
	s_waitcnt vmcnt(18)
	ds_write_b16 v98, v136
	ds_write_b16_d16_hi v98, v136 offset:144
	ds_write_b16 v98, v137 offset:288
	ds_write_b16_d16_hi v98, v137 offset:432
	ds_write_b16 v98, v138 offset:576
	ds_write_b16_d16_hi v98, v138 offset:720
	ds_write_b16 v98, v139 offset:864
	ds_write_b16_d16_hi v98, v139 offset:1008
	s_waitcnt vmcnt(17)
	ds_write_b16 v99, v140
	ds_write_b16_d16_hi v99, v140 offset:144
	ds_write_b16 v99, v141 offset:288
	ds_write_b16_d16_hi v99, v141 offset:432
	ds_write_b16 v99, v142 offset:576
	ds_write_b16_d16_hi v99, v142 offset:720
	ds_write_b16 v99, v143 offset:864
	ds_write_b16_d16_hi v99, v143 offset:1008
	s_waitcnt vmcnt(16)
	v_lshlrev_b32_e32 v6, 16, v146
	v_lshlrev_b32_e32 v12, 16, v145
	v_lshlrev_b32_e32 v10, 16, v144
	v_and_b32_e32 v13, 0xffff0000, v145
	v_and_b32_e32 v11, 0xffff0000, v144
	v_lshlrev_b32_e32 v8, 16, v147
	v_and_b32_e32 v9, 0xffff0000, v147
	v_and_b32_e32 v7, 0xffff0000, v146
	ds_write_b128 v100, v[10:13] offset:55296
	ds_write_b128 v100, v[6:9] offset:55312
	s_waitcnt vmcnt(15)
	v_lshlrev_b32_e32 v66, 16, v148
	s_waitcnt vmcnt(14)
	v_lshlrev_b32_e32 v67, 16, v149
	s_waitcnt vmcnt(13)
	v_lshlrev_b32_e32 v68, 16, v150
	s_waitcnt vmcnt(12)
	v_lshlrev_b32_e32 v69, 16, v151
	s_waitcnt vmcnt(11)
	v_lshlrev_b32_e32 v70, 16, v152
	s_waitcnt vmcnt(10)
	v_lshlrev_b32_e32 v71, 16, v153
	s_waitcnt vmcnt(9)
	v_lshlrev_b32_e32 v72, 16, v154
	s_waitcnt vmcnt(8)
	v_lshlrev_b32_e32 v73, 16, v155
	s_waitcnt vmcnt(7)
	v_lshlrev_b32_e32 v74, 16, v156
	s_waitcnt vmcnt(6)
	v_lshlrev_b32_e32 v75, 16, v157
	s_waitcnt vmcnt(5)
	v_lshlrev_b32_e32 v76, 16, v158
	s_waitcnt vmcnt(4)
	v_lshlrev_b32_e32 v77, 16, v159
	s_waitcnt vmcnt(3)
	v_lshlrev_b32_e32 v78, 16, v160
	s_waitcnt vmcnt(2)
	v_lshlrev_b32_e32 v79, 16, v161
	s_waitcnt vmcnt(1)
	v_lshlrev_b32_e32 v80, 16, v162
	s_waitcnt vmcnt(0)
	v_lshlrev_b32_e32 v81, 16, v163
	s_waitcnt lgkmcnt(0)
	s_barrier
	s_branch .LBB0_771
